# first rowwise phase: the 2x32 adaLN partial sums per column pair loaded in one batch (was 64 dependent load-wait-add round trips)
# baseline (speedup 1.0000x reference)
; __device__ __forceinline__ float mod_val(const Args& a, int l, int b, int idx, int col) {
;     const float* modp = (const float*)(a.ws + WS_MODP);
;     const int n = idx * DM + col;
;     float s = a.ada_b[l * NMODW + n];
; #pragma unroll
;     for (int kc = 0; kc < KCH; ++kc) s += modp[((size_t)(l * KCH + kc) * 8 + b) * NMODW + n];
;     return s;
; }
; __device__ __forceinline__ void rowwise_phase(const Args& a, LAS unsigned char* lds, bool from_partials, bool has_y, bool has_h, bool xin_bf, int xout_mode, ...
;     ...
;         for (int col = tid; col < DM; col += 512) {
;             if (from_partials) {
;                 if (has_y) vec[col] = mod_val(a, l_y, b, gate_idx, col) * g_post[col];
;                 if (has_h) { vec[DM + col] = g_pre[col] * (1.0f + mod_val(a, l_h, b, scale_idx, col)); vec[2 * DM + col] = mod_val(a, l_h, b, shift_idx, col); }
.LBB0_106:
	v_ashrrev_i32_e32 v5, 31, v1
	v_mov_b32_e32 v4, v1
	v_ashrrev_i32_e32 v3, 31, v0
	v_mov_b32_e32 v2, v0
	v_lshlrev_b64 v[2:3], 2, v[2:3]
	v_lshlrev_b64 v[6:7], 2, v[4:5]
	v_lshl_add_u64 v[8:9], s[76:77], 0, v[2:3]
	v_lshl_add_u64 v[12:13], s[76:77], 0, v[6:7]
	v_add_u32_e32 v1, 0x400, v1
	v_add_u32_e32 v0, 0x400, v0
	global_load_dword v4, v[8:9], off
	global_load_dword v5, v[12:13], off
	v_ashrrev_i32_e32 v9, 31, v1
	v_mov_b32_e32 v8, v1
	v_ashrrev_i32_e32 v13, 31, v0
	v_mov_b32_e32 v12, v0
	v_lshlrev_b64 v[12:13], 2, v[12:13]
	v_lshlrev_b64 v[8:9], 2, v[8:9]
	v_lshl_add_u64 v[14:15], s[68:69], 0, v[12:13]
	v_lshl_add_u64 v[16:17], s[68:69], 0, v[8:9]
	v_lshl_add_u64 v[12:13], s[22:23], 0, v[12:13]
	global_load_dword v14, v[14:15], off
	s_nop 0
	global_load_dword v15, v[16:17], off
	v_lshl_add_u64 v[8:9], s[22:23], 0, v[8:9]
	global_load_dword v16, v[12:13], off
	global_load_dword v17, v[8:9], off
	v_add_u32_e32 v10, -2, v10
	s_waitcnt vmcnt(0)
	v_pk_add_f32 v[14:15], v[14:15], v[16:17]
	v_add_co_u32_e32 v212, vcc, s5, v12
	s_nop 1
	v_addc_co_u32_e32 v213, vcc, 0, v13, vcc
	v_add_co_u32_e32 v214, vcc, s5, v8
	s_nop 1
	v_addc_co_u32_e32 v215, vcc, 0, v9, vcc
	global_load_dword v134, v[212:213], off
	global_load_dword v135, v[214:215], off
	v_add_co_u32_e32 v212, vcc, s30, v12
	s_nop 1
	v_addc_co_u32_e32 v213, vcc, 0, v13, vcc
	v_add_co_u32_e32 v214, vcc, s30, v8
	s_nop 1
	v_addc_co_u32_e32 v215, vcc, 0, v9, vcc
	global_load_dword v136, v[212:213], off
	global_load_dword v137, v[214:215], off
	v_add_co_u32_e32 v212, vcc, s31, v12
	s_nop 1
	v_addc_co_u32_e32 v213, vcc, 0, v13, vcc
	v_add_co_u32_e32 v214, vcc, s31, v8
	s_nop 1
	v_addc_co_u32_e32 v215, vcc, 0, v9, vcc
	global_load_dword v138, v[212:213], off
	global_load_dword v139, v[214:215], off
	v_add_co_u32_e32 v212, vcc, s34, v12
	s_nop 1
	v_addc_co_u32_e32 v213, vcc, 0, v13, vcc
	v_add_co_u32_e32 v214, vcc, s34, v8
	s_nop 1
	v_addc_co_u32_e32 v215, vcc, 0, v9, vcc
	global_load_dword v140, v[212:213], off
	global_load_dword v141, v[214:215], off
	v_add_co_u32_e32 v212, vcc, s35, v12
	s_nop 1
	v_addc_co_u32_e32 v213, vcc, 0, v13, vcc
	v_add_co_u32_e32 v214, vcc, s35, v8
	s_nop 1
	v_addc_co_u32_e32 v215, vcc, 0, v9, vcc
	global_load_dword v142, v[212:213], off
	global_load_dword v143, v[214:215], off
	v_add_co_u32_e32 v212, vcc, s42, v12
	s_nop 1
	v_addc_co_u32_e32 v213, vcc, 0, v13, vcc
	v_add_co_u32_e32 v214, vcc, s42, v8
	s_nop 1
	v_addc_co_u32_e32 v215, vcc, 0, v9, vcc
	global_load_dword v144, v[212:213], off
	global_load_dword v145, v[214:215], off
	v_add_co_u32_e32 v212, vcc, s43, v12
	s_nop 1
	v_addc_co_u32_e32 v213, vcc, 0, v13, vcc
	v_add_co_u32_e32 v214, vcc, s43, v8
	s_nop 1
	v_addc_co_u32_e32 v215, vcc, 0, v9, vcc
	global_load_dword v146, v[212:213], off
	global_load_dword v147, v[214:215], off
	v_add_co_u32_e32 v212, vcc, s44, v12
	s_nop 1
	v_addc_co_u32_e32 v213, vcc, 0, v13, vcc
	v_add_co_u32_e32 v214, vcc, s44, v8
	s_nop 1
	v_addc_co_u32_e32 v215, vcc, 0, v9, vcc
	global_load_dword v148, v[212:213], off
	global_load_dword v149, v[214:215], off
	v_add_co_u32_e32 v212, vcc, s45, v12
	s_nop 1
	v_addc_co_u32_e32 v213, vcc, 0, v13, vcc
	v_add_co_u32_e32 v214, vcc, s45, v8
	s_nop 1
	v_addc_co_u32_e32 v215, vcc, 0, v9, vcc
	global_load_dword v150, v[212:213], off
	global_load_dword v151, v[214:215], off
	v_add_co_u32_e32 v212, vcc, s46, v12
	s_nop 1
	v_addc_co_u32_e32 v213, vcc, 0, v13, vcc
	v_add_co_u32_e32 v214, vcc, s46, v8
	s_nop 1
	v_addc_co_u32_e32 v215, vcc, 0, v9, vcc
	global_load_dword v152, v[212:213], off
	global_load_dword v153, v[214:215], off
	v_add_co_u32_e32 v212, vcc, s47, v12
	s_nop 1
	v_addc_co_u32_e32 v213, vcc, 0, v13, vcc
	v_add_co_u32_e32 v214, vcc, s47, v8
	s_nop 1
	v_addc_co_u32_e32 v215, vcc, 0, v9, vcc
	global_load_dword v154, v[212:213], off
	global_load_dword v155, v[214:215], off
	v_add_co_u32_e32 v212, vcc, s48, v12
	s_nop 1
	v_addc_co_u32_e32 v213, vcc, 0, v13, vcc
	v_add_co_u32_e32 v214, vcc, s48, v8
	s_nop 1
	v_addc_co_u32_e32 v215, vcc, 0, v9, vcc
	global_load_dword v156, v[212:213], off
	global_load_dword v157, v[214:215], off
	v_add_co_u32_e32 v212, vcc, s49, v12
	s_nop 1
	v_addc_co_u32_e32 v213, vcc, 0, v13, vcc
	v_add_co_u32_e32 v214, vcc, s49, v8
	s_nop 1
	v_addc_co_u32_e32 v215, vcc, 0, v9, vcc
	global_load_dword v158, v[212:213], off
	global_load_dword v159, v[214:215], off
	v_add_co_u32_e32 v212, vcc, s50, v12
	s_nop 1
	v_addc_co_u32_e32 v213, vcc, 0, v13, vcc
	v_add_co_u32_e32 v214, vcc, s50, v8
	s_nop 1
	v_addc_co_u32_e32 v215, vcc, 0, v9, vcc
	global_load_dword v160, v[212:213], off
	global_load_dword v161, v[214:215], off
	v_add_co_u32_e32 v212, vcc, s51, v12
	s_nop 1
	v_addc_co_u32_e32 v213, vcc, 0, v13, vcc
	v_add_co_u32_e32 v214, vcc, s51, v8
	s_nop 1
	v_addc_co_u32_e32 v215, vcc, 0, v9, vcc
	global_load_dword v162, v[212:213], off
	global_load_dword v163, v[214:215], off
	v_add_co_u32_e32 v212, vcc, s52, v12
	s_nop 1
	v_addc_co_u32_e32 v213, vcc, 0, v13, vcc
	v_add_co_u32_e32 v214, vcc, s52, v8
	s_nop 1
	v_addc_co_u32_e32 v215, vcc, 0, v9, vcc
	global_load_dword v164, v[212:213], off
	global_load_dword v165, v[214:215], off
	v_add_co_u32_e32 v212, vcc, s53, v12
	s_nop 1
	v_addc_co_u32_e32 v213, vcc, 0, v13, vcc
	v_add_co_u32_e32 v214, vcc, s53, v8
	s_nop 1
	v_addc_co_u32_e32 v215, vcc, 0, v9, vcc
	global_load_dword v166, v[212:213], off
	global_load_dword v167, v[214:215], off
	v_add_co_u32_e32 v212, vcc, s54, v12
	s_nop 1
	v_addc_co_u32_e32 v213, vcc, 0, v13, vcc
	v_add_co_u32_e32 v214, vcc, s54, v8
	s_nop 1
	v_addc_co_u32_e32 v215, vcc, 0, v9, vcc
	global_load_dword v168, v[212:213], off
	global_load_dword v169, v[214:215], off
; __device__ __forceinline__ float mod_val(const Args& a, int l, int b, int idx, int col) {
;     ...
;     float s = a.ada_b[l * NMODW + n];
; #pragma unroll
;     for (int kc = 0; kc < KCH; ++kc) s += modp[((size_t)(l * KCH + kc) * 8 + b) * NMODW + n];
; __device__ __forceinline__ void rowwise_phase(const Args& a, LAS unsigned char* lds, bool from_partials, bool has_y, bool has_h, bool xin_bf, int xout_mode, ...
;     ...
;                 if (has_h) { vec[DM + col] = g_pre[col] * (1.0f + mod_val(a, l_h, b, scale_idx, col)); vec[2 * DM + col] = mod_val(a, l_h, b, shift_idx, col); }
	v_add_co_u32_e32 v212, vcc, s55, v12
	s_nop 1
	v_addc_co_u32_e32 v213, vcc, 0, v13, vcc
	v_add_co_u32_e32 v214, vcc, s55, v8
	s_nop 1
	v_addc_co_u32_e32 v215, vcc, 0, v9, vcc
	global_load_dword v170, v[212:213], off
	global_load_dword v171, v[214:215], off
	v_add_co_u32_e32 v212, vcc, s56, v12
	s_nop 1
	v_addc_co_u32_e32 v213, vcc, 0, v13, vcc
	v_add_co_u32_e32 v214, vcc, s56, v8
	s_nop 1
	v_addc_co_u32_e32 v215, vcc, 0, v9, vcc
	global_load_dword v172, v[212:213], off
	global_load_dword v173, v[214:215], off
	v_add_co_u32_e32 v212, vcc, s57, v12
	s_nop 1
	v_addc_co_u32_e32 v213, vcc, 0, v13, vcc
	v_add_co_u32_e32 v214, vcc, s57, v8
	s_nop 1
	v_addc_co_u32_e32 v215, vcc, 0, v9, vcc
	global_load_dword v174, v[212:213], off
	global_load_dword v175, v[214:215], off
	v_add_co_u32_e32 v212, vcc, s58, v12
	s_nop 1
	v_addc_co_u32_e32 v213, vcc, 0, v13, vcc
	v_add_co_u32_e32 v214, vcc, s58, v8
	s_nop 1
	v_addc_co_u32_e32 v215, vcc, 0, v9, vcc
	global_load_dword v176, v[212:213], off
	global_load_dword v177, v[214:215], off
	v_add_co_u32_e32 v212, vcc, s59, v12
	s_nop 1
	v_addc_co_u32_e32 v213, vcc, 0, v13, vcc
	v_add_co_u32_e32 v214, vcc, s59, v8
	s_nop 1
	v_addc_co_u32_e32 v215, vcc, 0, v9, vcc
	global_load_dword v178, v[212:213], off
	global_load_dword v179, v[214:215], off
	v_add_co_u32_e32 v212, vcc, s60, v12
	s_nop 1
	v_addc_co_u32_e32 v213, vcc, 0, v13, vcc
	v_add_co_u32_e32 v214, vcc, s60, v8
	s_nop 1
	v_addc_co_u32_e32 v215, vcc, 0, v9, vcc
	global_load_dword v180, v[212:213], off
	global_load_dword v181, v[214:215], off
	v_add_co_u32_e32 v212, vcc, s61, v12
	s_nop 1
	v_addc_co_u32_e32 v213, vcc, 0, v13, vcc
	v_add_co_u32_e32 v214, vcc, s61, v8
	s_nop 1
	v_addc_co_u32_e32 v215, vcc, 0, v9, vcc
	global_load_dword v182, v[212:213], off
	global_load_dword v183, v[214:215], off
	v_add_co_u32_e32 v212, vcc, s62, v12
	s_nop 1
	v_addc_co_u32_e32 v213, vcc, 0, v13, vcc
	v_add_co_u32_e32 v214, vcc, s62, v8
	s_nop 1
	v_addc_co_u32_e32 v215, vcc, 0, v9, vcc
	global_load_dword v184, v[212:213], off
	global_load_dword v185, v[214:215], off
	v_add_co_u32_e32 v212, vcc, s63, v12
	s_nop 1
	v_addc_co_u32_e32 v213, vcc, 0, v13, vcc
	v_add_co_u32_e32 v214, vcc, s63, v8
	s_nop 1
	v_addc_co_u32_e32 v215, vcc, 0, v9, vcc
	global_load_dword v186, v[212:213], off
	global_load_dword v187, v[214:215], off
	v_add_co_u32_e32 v212, vcc, s64, v12
	s_nop 1
	v_addc_co_u32_e32 v213, vcc, 0, v13, vcc
	v_add_co_u32_e32 v214, vcc, s64, v8
	s_nop 1
	v_addc_co_u32_e32 v215, vcc, 0, v9, vcc
	global_load_dword v188, v[212:213], off
	global_load_dword v189, v[214:215], off
	v_add_co_u32_e32 v212, vcc, s65, v12
	s_nop 1
	v_addc_co_u32_e32 v213, vcc, 0, v13, vcc
	v_add_co_u32_e32 v214, vcc, s65, v8
	s_nop 1
	v_addc_co_u32_e32 v215, vcc, 0, v9, vcc
	global_load_dword v190, v[212:213], off
	global_load_dword v191, v[214:215], off
	v_add_co_u32_e32 v212, vcc, s66, v12
	s_nop 1
	v_addc_co_u32_e32 v213, vcc, 0, v13, vcc
	v_add_co_u32_e32 v214, vcc, s66, v8
	s_nop 1
	v_addc_co_u32_e32 v215, vcc, 0, v9, vcc
	global_load_dword v208, v[212:213], off
	global_load_dword v209, v[214:215], off
	v_add_co_u32_e32 v212, vcc, s67, v12
	s_nop 1
	v_addc_co_u32_e32 v213, vcc, 0, v13, vcc
	v_add_co_u32_e32 v214, vcc, s67, v8
	s_nop 1
	v_addc_co_u32_e32 v215, vcc, 0, v9, vcc
	global_load_dword v210, v[212:213], off
	global_load_dword v211, v[214:215], off
	s_waitcnt vmcnt(0)
	s_nop 0
	v_pk_add_f32 v[14:15], v[14:15], v[134:135]
	s_nop 0
	v_pk_add_f32 v[14:15], v[14:15], v[136:137]
	s_nop 0
	v_pk_add_f32 v[14:15], v[14:15], v[138:139]
	s_nop 0
	v_pk_add_f32 v[14:15], v[14:15], v[140:141]
	s_nop 0
	v_pk_add_f32 v[14:15], v[14:15], v[142:143]
	s_nop 0
	v_pk_add_f32 v[14:15], v[14:15], v[144:145]
	s_nop 0
	v_pk_add_f32 v[14:15], v[14:15], v[146:147]
	s_nop 0
	v_pk_add_f32 v[14:15], v[14:15], v[148:149]
	s_nop 0
	v_pk_add_f32 v[14:15], v[14:15], v[150:151]
	s_nop 0
	v_pk_add_f32 v[14:15], v[14:15], v[152:153]
	s_nop 0
	v_pk_add_f32 v[14:15], v[14:15], v[154:155]
	s_nop 0
	v_pk_add_f32 v[14:15], v[14:15], v[156:157]
	s_nop 0
	v_pk_add_f32 v[14:15], v[14:15], v[158:159]
	s_nop 0
	v_pk_add_f32 v[14:15], v[14:15], v[160:161]
	s_nop 0
	v_pk_add_f32 v[14:15], v[14:15], v[162:163]
	s_nop 0
	v_pk_add_f32 v[14:15], v[14:15], v[164:165]
	s_nop 0
	v_pk_add_f32 v[14:15], v[14:15], v[166:167]
	s_nop 0
	v_pk_add_f32 v[14:15], v[14:15], v[168:169]
	s_nop 0
	v_pk_add_f32 v[14:15], v[14:15], v[170:171]
	s_nop 0
	v_pk_add_f32 v[14:15], v[14:15], v[172:173]
	s_nop 0
	v_pk_add_f32 v[14:15], v[14:15], v[174:175]
	s_nop 0
	v_pk_add_f32 v[14:15], v[14:15], v[176:177]
	s_nop 0
	v_pk_add_f32 v[14:15], v[14:15], v[178:179]
	s_nop 0
	v_pk_add_f32 v[14:15], v[14:15], v[180:181]
	s_nop 0
	v_pk_add_f32 v[14:15], v[14:15], v[182:183]
	s_nop 0
	v_pk_add_f32 v[14:15], v[14:15], v[184:185]
	s_nop 0
	v_pk_add_f32 v[14:15], v[14:15], v[186:187]
	s_nop 0
	v_pk_add_f32 v[14:15], v[14:15], v[188:189]
	s_nop 0
	v_pk_add_f32 v[14:15], v[14:15], v[190:191]
	s_nop 0
	v_pk_add_f32 v[14:15], v[14:15], v[208:209]
	s_nop 0
	v_pk_add_f32 v[14:15], v[14:15], v[210:211]
	s_nop 0
	v_pk_add_f32 v[8:9], v[14:15], 1.0 op_sel_hi:[1,0]
	s_nop 0
	v_pk_mul_f32 v[4:5], v[4:5], v[8:9]
	ds_write2st64_b32 v11, v4, v5 offset1:8
	v_lshl_add_u64 v[4:5], s[68:69], 0, v[2:3]
	v_lshl_add_u64 v[8:9], s[68:69], 0, v[6:7]
	global_load_dword v12, v[4:5], off
	global_load_dword v13, v[8:9], off
	v_lshl_add_u64 v[4:5], s[22:23], 0, v[2:3]
	v_lshl_add_u64 v[2:3], s[22:23], 0, v[6:7]
	global_load_dword v6, v[4:5], off
	global_load_dword v7, v[2:3], off
	s_waitcnt vmcnt(0)
; __device__ __forceinline__ float mod_val(const Args& a, int l, int b, int idx, int col) {
;     ...
;     float s = a.ada_b[l * NMODW + n];
; #pragma unroll
;     for (int kc = 0; kc < KCH; ++kc) s += modp[((size_t)(l * KCH + kc) * 8 + b) * NMODW + n];
; __device__ __forceinline__ void rowwise_phase(const Args& a, LAS unsigned char* lds, bool from_partials, bool has_y, bool has_h, bool xin_bf, int xout_mode, ...
;     ...
;                 if (has_h) { vec[DM + col] = g_pre[col] * (1.0f + mod_val(a, l_h, b, scale_idx, col)); vec[2 * DM + col] = mod_val(a, l_h, b, shift_idx, col); }
	v_pk_add_f32 v[6:7], v[12:13], v[6:7]
	v_add_co_u32_e32 v212, vcc, s5, v4
	s_nop 1
	v_addc_co_u32_e32 v213, vcc, 0, v5, vcc
	v_add_co_u32_e32 v214, vcc, s5, v2
	s_nop 1
	v_addc_co_u32_e32 v215, vcc, 0, v3, vcc
	global_load_dword v134, v[212:213], off
	global_load_dword v135, v[214:215], off
	v_add_co_u32_e32 v212, vcc, s30, v4
	s_nop 1
	v_addc_co_u32_e32 v213, vcc, 0, v5, vcc
	v_add_co_u32_e32 v214, vcc, s30, v2
	s_nop 1
	v_addc_co_u32_e32 v215, vcc, 0, v3, vcc
	global_load_dword v136, v[212:213], off
	global_load_dword v137, v[214:215], off
	v_add_co_u32_e32 v212, vcc, s31, v4
	s_nop 1
	v_addc_co_u32_e32 v213, vcc, 0, v5, vcc
	v_add_co_u32_e32 v214, vcc, s31, v2
	s_nop 1
	v_addc_co_u32_e32 v215, vcc, 0, v3, vcc
	global_load_dword v138, v[212:213], off
	global_load_dword v139, v[214:215], off
	v_add_co_u32_e32 v212, vcc, s34, v4
	s_nop 1
	v_addc_co_u32_e32 v213, vcc, 0, v5, vcc
	v_add_co_u32_e32 v214, vcc, s34, v2
	s_nop 1
	v_addc_co_u32_e32 v215, vcc, 0, v3, vcc
	global_load_dword v140, v[212:213], off
	global_load_dword v141, v[214:215], off
	v_add_co_u32_e32 v212, vcc, s35, v4
	s_nop 1
	v_addc_co_u32_e32 v213, vcc, 0, v5, vcc
	v_add_co_u32_e32 v214, vcc, s35, v2
	s_nop 1
	v_addc_co_u32_e32 v215, vcc, 0, v3, vcc
	global_load_dword v142, v[212:213], off
	global_load_dword v143, v[214:215], off
	v_add_co_u32_e32 v212, vcc, s42, v4
	s_nop 1
	v_addc_co_u32_e32 v213, vcc, 0, v5, vcc
	v_add_co_u32_e32 v214, vcc, s42, v2
	s_nop 1
	v_addc_co_u32_e32 v215, vcc, 0, v3, vcc
	global_load_dword v144, v[212:213], off
	global_load_dword v145, v[214:215], off
	v_add_co_u32_e32 v212, vcc, s43, v4
	s_nop 1
	v_addc_co_u32_e32 v213, vcc, 0, v5, vcc
	v_add_co_u32_e32 v214, vcc, s43, v2
	s_nop 1
	v_addc_co_u32_e32 v215, vcc, 0, v3, vcc
	global_load_dword v146, v[212:213], off
	global_load_dword v147, v[214:215], off
	v_add_co_u32_e32 v212, vcc, s44, v4
	s_nop 1
	v_addc_co_u32_e32 v213, vcc, 0, v5, vcc
	v_add_co_u32_e32 v214, vcc, s44, v2
	s_nop 1
	v_addc_co_u32_e32 v215, vcc, 0, v3, vcc
	global_load_dword v148, v[212:213], off
	global_load_dword v149, v[214:215], off
	v_add_co_u32_e32 v212, vcc, s45, v4
	s_nop 1
	v_addc_co_u32_e32 v213, vcc, 0, v5, vcc
	v_add_co_u32_e32 v214, vcc, s45, v2
	s_nop 1
	v_addc_co_u32_e32 v215, vcc, 0, v3, vcc
	global_load_dword v150, v[212:213], off
	global_load_dword v151, v[214:215], off
	v_add_co_u32_e32 v212, vcc, s46, v4
	s_nop 1
	v_addc_co_u32_e32 v213, vcc, 0, v5, vcc
	v_add_co_u32_e32 v214, vcc, s46, v2
	s_nop 1
	v_addc_co_u32_e32 v215, vcc, 0, v3, vcc
	global_load_dword v152, v[212:213], off
	global_load_dword v153, v[214:215], off
	v_add_co_u32_e32 v212, vcc, s47, v4
	s_nop 1
	v_addc_co_u32_e32 v213, vcc, 0, v5, vcc
	v_add_co_u32_e32 v214, vcc, s47, v2
	s_nop 1
	v_addc_co_u32_e32 v215, vcc, 0, v3, vcc
	global_load_dword v154, v[212:213], off
	global_load_dword v155, v[214:215], off
	v_add_co_u32_e32 v212, vcc, s48, v4
	s_nop 1
	v_addc_co_u32_e32 v213, vcc, 0, v5, vcc
	v_add_co_u32_e32 v214, vcc, s48, v2
	s_nop 1
	v_addc_co_u32_e32 v215, vcc, 0, v3, vcc
	global_load_dword v156, v[212:213], off
	global_load_dword v157, v[214:215], off
	v_add_co_u32_e32 v212, vcc, s49, v4
	s_nop 1
	v_addc_co_u32_e32 v213, vcc, 0, v5, vcc
	v_add_co_u32_e32 v214, vcc, s49, v2
	s_nop 1
	v_addc_co_u32_e32 v215, vcc, 0, v3, vcc
	global_load_dword v158, v[212:213], off
	global_load_dword v159, v[214:215], off
	v_add_co_u32_e32 v212, vcc, s50, v4
	s_nop 1
	v_addc_co_u32_e32 v213, vcc, 0, v5, vcc
	v_add_co_u32_e32 v214, vcc, s50, v2
	s_nop 1
	v_addc_co_u32_e32 v215, vcc, 0, v3, vcc
	global_load_dword v160, v[212:213], off
	global_load_dword v161, v[214:215], off
	v_add_co_u32_e32 v212, vcc, s51, v4
	s_nop 1
	v_addc_co_u32_e32 v213, vcc, 0, v5, vcc
	v_add_co_u32_e32 v214, vcc, s51, v2
	s_nop 1
	v_addc_co_u32_e32 v215, vcc, 0, v3, vcc
	global_load_dword v162, v[212:213], off
	global_load_dword v163, v[214:215], off
	v_add_co_u32_e32 v212, vcc, s52, v4
	s_nop 1
	v_addc_co_u32_e32 v213, vcc, 0, v5, vcc
	v_add_co_u32_e32 v214, vcc, s52, v2
	s_nop 1
	v_addc_co_u32_e32 v215, vcc, 0, v3, vcc
	global_load_dword v164, v[212:213], off
	global_load_dword v165, v[214:215], off
	v_add_co_u32_e32 v212, vcc, s53, v4
	s_nop 1
	v_addc_co_u32_e32 v213, vcc, 0, v5, vcc
	v_add_co_u32_e32 v214, vcc, s53, v2
	s_nop 1
	v_addc_co_u32_e32 v215, vcc, 0, v3, vcc
	global_load_dword v166, v[212:213], off
	global_load_dword v167, v[214:215], off
	v_add_co_u32_e32 v212, vcc, s54, v4
	s_nop 1
	v_addc_co_u32_e32 v213, vcc, 0, v5, vcc
	v_add_co_u32_e32 v214, vcc, s54, v2
	s_nop 1
	v_addc_co_u32_e32 v215, vcc, 0, v3, vcc
	global_load_dword v168, v[212:213], off
	global_load_dword v169, v[214:215], off
	v_add_co_u32_e32 v212, vcc, s55, v4
	s_nop 1
	v_addc_co_u32_e32 v213, vcc, 0, v5, vcc
	v_add_co_u32_e32 v214, vcc, s55, v2
	s_nop 1
	v_addc_co_u32_e32 v215, vcc, 0, v3, vcc
	global_load_dword v170, v[212:213], off
	global_load_dword v171, v[214:215], off
	v_add_co_u32_e32 v212, vcc, s56, v4
	s_nop 1
	v_addc_co_u32_e32 v213, vcc, 0, v5, vcc
	v_add_co_u32_e32 v214, vcc, s56, v2
	s_nop 1
; __device__ __forceinline__ float mod_val(const Args& a, int l, int b, int idx, int col) {
;     ...
;     float s = a.ada_b[l * NMODW + n];
; #pragma unroll
;     for (int kc = 0; kc < KCH; ++kc) s += modp[((size_t)(l * KCH + kc) * 8 + b) * NMODW + n];
; __device__ __forceinline__ void rowwise_phase(const Args& a, LAS unsigned char* lds, bool from_partials, bool has_y, bool has_h, bool xin_bf, int xout_mode, ...
;     ...
;         for (int col = tid; col < DM; col += 512) {
;             if (from_partials) {
;                 if (has_y) vec[col] = mod_val(a, l_y, b, gate_idx, col) * g_post[col];
;                 if (has_h) { vec[DM + col] = g_pre[col] * (1.0f + mod_val(a, l_h, b, scale_idx, col)); vec[2 * DM + col] = mod_val(a, l_h, b, shift_idx, col); }
	v_addc_co_u32_e32 v215, vcc, 0, v3, vcc
	global_load_dword v172, v[212:213], off
	global_load_dword v173, v[214:215], off
	v_add_co_u32_e32 v212, vcc, s57, v4
	s_nop 1
	v_addc_co_u32_e32 v213, vcc, 0, v5, vcc
	v_add_co_u32_e32 v214, vcc, s57, v2
	s_nop 1
	v_addc_co_u32_e32 v215, vcc, 0, v3, vcc
	global_load_dword v174, v[212:213], off
	global_load_dword v175, v[214:215], off
	v_add_co_u32_e32 v212, vcc, s58, v4
	s_nop 1
	v_addc_co_u32_e32 v213, vcc, 0, v5, vcc
	v_add_co_u32_e32 v214, vcc, s58, v2
	s_nop 1
	v_addc_co_u32_e32 v215, vcc, 0, v3, vcc
	global_load_dword v176, v[212:213], off
	global_load_dword v177, v[214:215], off
	v_add_co_u32_e32 v212, vcc, s59, v4
	s_nop 1
	v_addc_co_u32_e32 v213, vcc, 0, v5, vcc
	v_add_co_u32_e32 v214, vcc, s59, v2
	s_nop 1
	v_addc_co_u32_e32 v215, vcc, 0, v3, vcc
	global_load_dword v178, v[212:213], off
	global_load_dword v179, v[214:215], off
	v_add_co_u32_e32 v212, vcc, s60, v4
	s_nop 1
	v_addc_co_u32_e32 v213, vcc, 0, v5, vcc
	v_add_co_u32_e32 v214, vcc, s60, v2
	s_nop 1
	v_addc_co_u32_e32 v215, vcc, 0, v3, vcc
	global_load_dword v180, v[212:213], off
	global_load_dword v181, v[214:215], off
	v_add_co_u32_e32 v212, vcc, s61, v4
	s_nop 1
	v_addc_co_u32_e32 v213, vcc, 0, v5, vcc
	v_add_co_u32_e32 v214, vcc, s61, v2
	s_nop 1
	v_addc_co_u32_e32 v215, vcc, 0, v3, vcc
	global_load_dword v182, v[212:213], off
	global_load_dword v183, v[214:215], off
	v_add_co_u32_e32 v212, vcc, s62, v4
	s_nop 1
	v_addc_co_u32_e32 v213, vcc, 0, v5, vcc
	v_add_co_u32_e32 v214, vcc, s62, v2
	s_nop 1
	v_addc_co_u32_e32 v215, vcc, 0, v3, vcc
	global_load_dword v184, v[212:213], off
	global_load_dword v185, v[214:215], off
	v_add_co_u32_e32 v212, vcc, s63, v4
	s_nop 1
	v_addc_co_u32_e32 v213, vcc, 0, v5, vcc
	v_add_co_u32_e32 v214, vcc, s63, v2
	s_nop 1
	v_addc_co_u32_e32 v215, vcc, 0, v3, vcc
	global_load_dword v186, v[212:213], off
	global_load_dword v187, v[214:215], off
	v_add_co_u32_e32 v212, vcc, s64, v4
	s_nop 1
	v_addc_co_u32_e32 v213, vcc, 0, v5, vcc
	v_add_co_u32_e32 v214, vcc, s64, v2
	s_nop 1
	v_addc_co_u32_e32 v215, vcc, 0, v3, vcc
	global_load_dword v188, v[212:213], off
	global_load_dword v189, v[214:215], off
	v_add_co_u32_e32 v212, vcc, s65, v4
	s_nop 1
	v_addc_co_u32_e32 v213, vcc, 0, v5, vcc
	v_add_co_u32_e32 v214, vcc, s65, v2
	s_nop 1
	v_addc_co_u32_e32 v215, vcc, 0, v3, vcc
	global_load_dword v190, v[212:213], off
	global_load_dword v191, v[214:215], off
	v_add_co_u32_e32 v212, vcc, s66, v4
	s_nop 1
	v_addc_co_u32_e32 v213, vcc, 0, v5, vcc
	v_add_co_u32_e32 v214, vcc, s66, v2
	s_nop 1
	v_addc_co_u32_e32 v215, vcc, 0, v3, vcc
	global_load_dword v208, v[212:213], off
	global_load_dword v209, v[214:215], off
	v_add_co_u32_e32 v212, vcc, s67, v4
	s_nop 1
	v_addc_co_u32_e32 v213, vcc, 0, v5, vcc
	v_add_co_u32_e32 v214, vcc, s67, v2
	s_nop 1
	v_addc_co_u32_e32 v215, vcc, 0, v3, vcc
	global_load_dword v210, v[212:213], off
	global_load_dword v211, v[214:215], off
	v_cmp_eq_u32_e32 vcc, 0, v10
	s_or_b64 s[24:25], vcc, s[24:25]
	s_waitcnt vmcnt(0)
	s_nop 0
	v_pk_add_f32 v[6:7], v[6:7], v[134:135]
	s_nop 0
	v_pk_add_f32 v[6:7], v[6:7], v[136:137]
	s_nop 0
	v_pk_add_f32 v[6:7], v[6:7], v[138:139]
	s_nop 0
	v_pk_add_f32 v[6:7], v[6:7], v[140:141]
	s_nop 0
	v_pk_add_f32 v[6:7], v[6:7], v[142:143]
	s_nop 0
	v_pk_add_f32 v[6:7], v[6:7], v[144:145]
	s_nop 0
	v_pk_add_f32 v[6:7], v[6:7], v[146:147]
	s_nop 0
	v_pk_add_f32 v[6:7], v[6:7], v[148:149]
	s_nop 0
	v_pk_add_f32 v[6:7], v[6:7], v[150:151]
	s_nop 0
	v_pk_add_f32 v[6:7], v[6:7], v[152:153]
	s_nop 0
	v_pk_add_f32 v[6:7], v[6:7], v[154:155]
	s_nop 0
	v_pk_add_f32 v[6:7], v[6:7], v[156:157]
	s_nop 0
	v_pk_add_f32 v[6:7], v[6:7], v[158:159]
	s_nop 0
	v_pk_add_f32 v[6:7], v[6:7], v[160:161]
	s_nop 0
	v_pk_add_f32 v[6:7], v[6:7], v[162:163]
	s_nop 0
	v_pk_add_f32 v[6:7], v[6:7], v[164:165]
	s_nop 0
	v_pk_add_f32 v[6:7], v[6:7], v[166:167]
	s_nop 0
	v_pk_add_f32 v[6:7], v[6:7], v[168:169]
	s_nop 0
	v_pk_add_f32 v[6:7], v[6:7], v[170:171]
	s_nop 0
	v_pk_add_f32 v[6:7], v[6:7], v[172:173]
	s_nop 0
	v_pk_add_f32 v[6:7], v[6:7], v[174:175]
	s_nop 0
	v_pk_add_f32 v[6:7], v[6:7], v[176:177]
	s_nop 0
	v_pk_add_f32 v[6:7], v[6:7], v[178:179]
	s_nop 0
	v_pk_add_f32 v[6:7], v[6:7], v[180:181]
	s_nop 0
	v_pk_add_f32 v[6:7], v[6:7], v[182:183]
	s_nop 0
	v_pk_add_f32 v[6:7], v[6:7], v[184:185]
	s_nop 0
	v_pk_add_f32 v[6:7], v[6:7], v[186:187]
	s_nop 0
	v_pk_add_f32 v[6:7], v[6:7], v[188:189]
	s_nop 0
	v_pk_add_f32 v[6:7], v[6:7], v[190:191]
	s_nop 0
	v_pk_add_f32 v[6:7], v[6:7], v[208:209]
	s_nop 0
	v_pk_add_f32 v[2:3], v[6:7], v[210:211]
	v_add_u32_e32 v4, 0x1000, v11
	ds_write2st64_b32 v11, v2, v3 offset0:16 offset1:24
	v_mov_b32_e32 v11, v4
	s_andn2_b64 exec, exec, s[24:25]
	s_cbranch_execnz .LBB0_106
	s_or_b64 exec, exec, s[24:25]
	s_mov_b64 s[16:17], 0
	s_and_saveexec_b64 s[22:23], s[40:41]
	s_mov_b64 s[16:17], exec
	v_lshlrev_b32_e32 v1, 2, v61
	s_or_b64 exec, exec, s[22:23]
	v_readlane_b32 s84, v246, 9
	s_orn2_b64 s[16:17], s[16:17], exec
	v_mov_b32_e32 v0, v61
	v_readlane_b32 s85, v246, 10
